# layer 0 mixer phase: the neighbourhood units of attention workgroups 0-23 (which also run the context-query units) move to hgrn workgroups 192-215, which have slack
# baseline (speedup 1.0000x reference)
.LBB0_592:
	s_setprio 0
	v_readlane_b32 s0, v252, 32
	v_readlane_b32 s1, v252, 33
	s_andn2_b64 vcc, exec, s[0:1]
	s_barrier
	s_cbranch_vccnz .LBB0_698
	v_readlane_b32 s0, v254, 8
	v_readlane_b32 s2, v254, 10
	v_readlane_b32 s3, v254, 11
	s_add_u32 s12, s2, 0x5600800
	s_addc_u32 s13, s3, 0
	s_add_u32 s14, s2, 0x5600b00
	s_addc_u32 s15, s3, 0
	v_readlane_b32 s16, v252, 31
	v_readlane_b32 s4, v254, 44
	s_nop 3
	s_cmp_eq_u32 s4, 3
	s_cbranch_scc0 .Lnas_hg
	s_sub_i32 s4, s78, 0xc0
	s_cmp_lt_u32 s4, 24
	s_cselect_b32 s16, s4, s16
.Lnas_hg:
	v_readlane_b32 s1, v254, 9
	s_branch .LBB0_595
.LBB0_594:
	s_or_b64 exec, exec, s[0:1]
	s_waitcnt lgkmcnt(0)
	ds_read_b128 v[36:39], v34 offset:49280
	ds_read_b128 v[40:43], v34 offset:49312
	s_lshl_b64 s[0:1], s[2:3], 11
	s_add_u32 s0, s54, s0
	s_addc_u32 s1, s55, s1
	s_waitcnt lgkmcnt(1)
	v_rcp_f32_e32 v0, v36
	v_rcp_f32_e32 v35, v37
	v_rcp_f32_e32 v44, v38
	v_rcp_f32_e32 v45, v39
	s_waitcnt lgkmcnt(0)
	v_rcp_f32_e32 v46, v40
	ds_read_b128 v[36:39], v34 offset:49344
	v_rcp_f32_e32 v47, v41
	v_rcp_f32_e32 v48, v42
	v_rcp_f32_e32 v49, v43
	ds_read_b128 v[40:43], v34 offset:49376
	s_add_u32 s2, s0, s36
	s_addc_u32 s3, s1, s37
	s_lshl_b32 s4, s17, 12
	s_waitcnt lgkmcnt(1)
	v_rcp_f32_e32 v34, v36
	v_rcp_f32_e32 v36, v37
	v_rcp_f32_e32 v37, v38
	v_rcp_f32_e32 v38, v39
	s_waitcnt lgkmcnt(0)
	v_rcp_f32_e32 v39, v40
	v_rcp_f32_e32 v40, v41
	v_rcp_f32_e32 v41, v42
	v_rcp_f32_e32 v42, v43
	s_lshl_b64 s[0:1], s[44:45], 11
	s_add_i32 s4, s4, 0
	v_lshlrev_b32_e32 v43, 9, v181
	v_lshlrev_b32_e32 v50, 1, v180
	v_mul_f32_e32 v2, v2, v0
	v_mul_f32_e32 v0, v18, v0
	v_add3_u32 v43, s4, v43, v50
	v_cvt_pk_bf16_f32 v0, v0, s0
	ds_write_b16 v43, v0 offset:51264
	v_mul_f32_e32 v0, v3, v35
	v_cvt_pk_bf16_f32 v0, v0, s0
	ds_write_b16 v43, v0 offset:51328
	v_mul_f32_e32 v0, v19, v35
	v_cvt_pk_bf16_f32 v0, v0, s0
	ds_write_b16 v43, v0 offset:51392
	v_mul_f32_e32 v0, v4, v44
	v_cvt_pk_bf16_f32 v0, v0, s0
	ds_write_b16 v43, v0 offset:51456
	v_mul_f32_e32 v0, v20, v44
	v_cvt_pk_bf16_f32 v0, v0, s0
	ds_write_b16 v43, v0 offset:51520
	v_mul_f32_e32 v0, v5, v45
	v_cvt_pk_bf16_f32 v0, v0, s0
	ds_write_b16 v43, v0 offset:51584
	v_mul_f32_e32 v0, v21, v45
	v_cvt_pk_bf16_f32 v0, v0, s0
	ds_write_b16 v43, v0 offset:51648
	v_mul_f32_e32 v0, v6, v46
	v_cvt_pk_bf16_f32 v0, v0, s0
	ds_write_b16 v43, v0 offset:52224
	v_mul_f32_e32 v0, v22, v46
	v_cvt_pk_bf16_f32 v0, v0, s0
	ds_write_b16 v43, v0 offset:52288
	v_mul_f32_e32 v0, v7, v47
	v_cvt_pk_bf16_f32 v0, v0, s0
	ds_write_b16 v43, v0 offset:52352
	v_mul_f32_e32 v0, v23, v47
	v_cvt_pk_bf16_f32 v0, v0, s0
	ds_write_b16 v43, v0 offset:52416
	v_mul_f32_e32 v0, v8, v48
	v_cvt_pk_bf16_f32 v0, v0, s0
	ds_write_b16 v43, v0 offset:52480
	v_mul_f32_e32 v0, v24, v48
	v_cvt_pk_bf16_f32 v0, v0, s0
	ds_write_b16 v43, v0 offset:52544
	v_mul_f32_e32 v0, v9, v49
	v_cvt_pk_bf16_f32 v0, v0, s0
	ds_write_b16 v43, v0 offset:52608
	v_mul_f32_e32 v0, v25, v49
	v_cvt_pk_bf16_f32 v0, v0, s0
	ds_write_b16 v43, v0 offset:52672
	v_mul_f32_e32 v0, v10, v34
	v_cvt_pk_bf16_f32 v0, v0, s0
	ds_write_b16 v43, v0 offset:53248
	v_mul_f32_e32 v0, v26, v34
	v_cvt_pk_bf16_f32 v0, v0, s0
	ds_write_b16 v43, v0 offset:53312
	v_mul_f32_e32 v0, v11, v36
	v_cvt_pk_bf16_f32 v0, v0, s0
	ds_write_b16 v43, v0 offset:53376
	v_mul_f32_e32 v0, v27, v36
	v_cvt_pk_bf16_f32 v0, v0, s0
	ds_write_b16 v43, v0 offset:53440
	v_mul_f32_e32 v0, v12, v37
	v_cvt_pk_bf16_f32 v0, v0, s0
	ds_write_b16 v43, v0 offset:53504
	v_mul_f32_e32 v0, v28, v37
	v_cvt_pk_bf16_f32 v0, v0, s0
	ds_write_b16 v43, v0 offset:53568
	v_mul_f32_e32 v0, v13, v38
	v_cvt_pk_bf16_f32 v0, v0, s0
	ds_write_b16 v43, v0 offset:53632
	v_mul_f32_e32 v0, v29, v38
	v_cvt_pk_bf16_f32 v0, v0, s0
	ds_write_b16 v43, v0 offset:53696
	v_mul_f32_e32 v0, v14, v39
	v_cvt_pk_bf16_f32 v0, v0, s0
	ds_write_b16 v43, v0 offset:54272
	v_mul_f32_e32 v0, v30, v39
	v_cvt_pk_bf16_f32 v0, v0, s0
	ds_write_b16 v43, v0 offset:54336
	v_mul_f32_e32 v0, v15, v40
	v_cvt_pk_bf16_f32 v0, v0, s0
	ds_write_b16 v43, v0 offset:54400
	v_mul_f32_e32 v0, v31, v40
	v_cvt_pk_bf16_f32 v0, v0, s0
	ds_write_b16 v43, v0 offset:54464
	v_mul_f32_e32 v0, v16, v41
	v_cvt_pk_bf16_f32 v0, v0, s0
	ds_write_b16 v43, v0 offset:54528
	v_mul_f32_e32 v0, v32, v41
	v_cvt_pk_bf16_f32 v0, v0, s0
	ds_write_b16 v43, v0 offset:54592
	v_mul_f32_e32 v0, v17, v42
	v_cvt_pk_bf16_f32 v0, v0, s0
	ds_write_b16 v43, v0 offset:54656
	v_mul_f32_e32 v0, v33, v42
	v_cvt_pk_bf16_f32 v0, v0, s0
	ds_write_b16 v43, v0 offset:54720
	v_lshlrev_b32_e32 v0, 1, v179
	v_cvt_pk_bf16_f32 v2, v2, s0
	s_add_u32 s0, s2, s0
	v_and_b32_e32 v0, 0x70, v0
	ds_write_b16 v43, v2 offset:51200
	s_addc_u32 s1, s3, s1
	v_lshrrev_b32_e32 v14, 3, v178
	v_add_u32_e32 v15, s4, v0
	s_waitcnt lgkmcnt(0)
	v_lshl_add_u64 v[10:11], s[0:1], 0, v[0:1]
	v_lshl_add_u32 v0, v14, 7, v15
	v_or_b32_e32 v16, 8, v14
	ds_read_b128 v[2:5], v0 offset:51200
	v_lshl_add_u32 v6, v16, 7, v15
	ds_read_b128 v[6:9], v6 offset:51200
	v_lshlrev_b32_e32 v0, 11, v14
	v_lshl_add_u64 v[12:13], v[10:11], 0, v[0:1]
	v_lshlrev_b32_e32 v0, 11, v16
	s_waitcnt lgkmcnt(1)
	global_store_dwordx4 v[12:13], v[2:5], off offset:1280
	v_readlane_b32 s0, v252, 29
	s_cmpk_lt_i32 s16, 0xc0
	s_cselect_b32 s0, 0xc0, s0
	s_add_i32 s16, s16, s0
	v_lshl_add_u64 v[2:3], v[10:11], 0, v[0:1]
	v_or_b32_e32 v0, 16, v14
	s_waitcnt lgkmcnt(0)
	global_store_dwordx4 v[2:3], v[6:9], off offset:1280
	v_lshl_add_u32 v2, v0, 7, v15
	v_or_b32_e32 v14, 24, v14
	ds_read_b128 v[2:5], v2 offset:51200
	v_lshl_add_u32 v6, v14, 7, v15
	ds_read_b128 v[6:9], v6 offset:51200
	v_lshlrev_b32_e32 v0, 11, v0
	v_lshl_add_u64 v[12:13], v[10:11], 0, v[0:1]
	v_lshlrev_b32_e32 v0, 11, v14
	s_waitcnt lgkmcnt(1)
	global_store_dwordx4 v[12:13], v[2:5], off offset:1280
	s_cmpk_gt_i32 s16, 0x17f
	s_nop 0
	v_lshl_add_u64 v[2:3], v[10:11], 0, v[0:1]
	s_waitcnt lgkmcnt(0)
	global_store_dwordx4 v[2:3], v[6:9], off offset:1280
	s_waitcnt lgkmcnt(0)
	s_barrier
	s_cbranch_scc1 .LBB0_698

.Ll4acq_done_n:
	v_readlane_b32 s0, v255, 40
	v_readlane_b32 s1, v255, 41
	v_readlane_b32 s2, v255, 42
	v_readlane_b32 s3, v255, 43
	v_readlane_b32 s4, v255, 44
	s_nop 3
	v_readlane_b32 s0, v252, 37
	v_readlane_b32 s1, v252, 38
	s_andn2_b64 vcc, exec, s[0:1]
	s_cbranch_vccnz .LBB0_870
	v_readlane_b32 s0, v254, 44
	s_nop 3
	s_cmp_eq_u32 s0, 3
	s_cbranch_scc0 .Lnas_att
	s_cmpk_lt_i32 s78, 24
	s_cbranch_scc1 .LBB0_870
.Lnas_att:
	v_readlane_b32 s0, v254, 8
	v_readlane_b32 s2, v254, 10
	v_readlane_b32 s3, v254, 11
	s_add_u32 s12, s2, 0x5600800
	s_addc_u32 s13, s3, 0
	s_add_u32 s14, s2, 0x5600b00
	s_addc_u32 s15, s3, 0
	s_mov_b32 s16, s78
	v_readlane_b32 s1, v254, 9
	s_branch .LBB0_767
